# P0 rmsnorm/quantize row loop: sum and max wave reductions via DPP row ops + permlane swaps instead of twelve ds_bpermute round trips
# baseline (speedup 1.0000x reference)
; __device__ __forceinline__ float wave_sum(float v) {
; #pragma unroll
;     for (int o = 1; o < 64; o <<= 1) v += __shfl_xor(v, o);
;     return v;
; }
; __device__ __forceinline__ void p0_prep(Frame& F) {
;     ...
;       for (int t = gw; t < NT_TOK; t += NGW) {
;           { const int tn = (t + NGW < NT_TOK) ? t + NGW : t; const float* xn_ = P0_XROW(tn);
; #pragma unroll
;             for (int j = 0; j < 4; ++j) { nxt[j][0] = *(const f32x4*)(xn_ + 512 * j); nxt[j][1] = *(const f32x4*)(xn_ + 512 * j + 4); } }
;           float s = 0.f;
; #pragma unroll
;           for (int j = 0; j < 4; ++j)
; #pragma unroll
;               for (int q = 0; q < 2; ++q) s += (cur[j][q][0] * cur[j][q][0] + cur[j][q][1] * cur[j][q][1]) + (cur[j][q][2] * cur[j][q][2] + cur[j][q][3] * cur[j][q][3]);
;           const float rstd = 1.0f / sqrtf(wave_sum(s) * (1.0f / DM) + RMS_EPS);
;     ...
;           if (lane == 0) ((float*)(F.ws + WS_SX2))[t] = 6.0f / (127.0f * rstd);
.LBB0_29:
	s_add_i32 s27, s20, s56
	s_cmpk_gt_i32 s27, 0x5fff
	s_cselect_b64 s[18:19], -1, 0
	s_cmpk_lt_i32 s27, 0x6000
	s_cselect_b32 s6, s27, s20
	s_add_i32 s21, s6, 0xffffc000
	s_ashr_i32 s7, s6, 31
	s_cmpk_lt_i32 s6, 0x4000
	v_readlane_b32 s36, v254, 7
	s_waitcnt vmcnt(6)
	v_mul_f32_e32 v100, v93, v93
	v_mul_f32_e32 v101, v95, v95
	s_cselect_b32 s7, s7, 0
	s_cselect_b32 s6, s6, s21
	v_readlane_b32 s37, v254, 8
	v_readlane_b32 s38, v254, 9
	v_readlane_b32 s39, v254, 10
	v_fmac_f32_e32 v100, v92, v92
	v_fmac_f32_e32 v101, v94, v94
	s_cselect_b32 s21, s37, s39
	s_cselect_b32 s28, s36, s38
	s_lshl_b64 s[6:7], s[6:7], 13
	v_add_f32_e32 v100, v100, v101
	v_mul_f32_e32 v101, v85, v85
	v_mul_f32_e32 v102, v87, v87
	s_add_u32 s6, s28, s6
	v_fmac_f32_e32 v101, v84, v84
	v_fmac_f32_e32 v102, v86, v86
	s_addc_u32 s7, s21, s7
	v_add_f32_e32 v101, v101, v102
	v_lshl_add_u64 v[56:57], v[96:97], 2, s[6:7]
	v_add_f32_e32 v100, v100, v101
	s_waitcnt vmcnt(4)
	v_mul_f32_e32 v101, v89, v89
	v_mul_f32_e32 v102, v91, v91
	global_load_dwordx4 v[36:39], v[56:57], off offset:16
	global_load_dwordx4 v[44:47], v[56:57], off
	global_load_dwordx4 v[32:35], v[56:57], off offset:2064
	global_load_dwordx4 v[40:43], v[56:57], off offset:2048
	v_add_co_u32_e32 v58, vcc, s22, v56
	v_fmac_f32_e32 v101, v88, v88
	v_fmac_f32_e32 v102, v90, v90
	v_lshl_add_u64 v[48:49], v[56:57], 0, s[2:3]
	v_addc_co_u32_e32 v59, vcc, 0, v57, vcc
	v_lshl_add_u64 v[56:57], v[56:57], 0, s[10:11]
	v_add_f32_e32 v101, v101, v102
	global_load_dwordx4 v[52:55], v[58:59], off
	s_nop 0
	global_load_dwordx4 v[48:51], v[48:49], off offset:16
	s_nop 0
	global_load_dwordx4 v[60:63], v[58:59], off offset:2048
	s_nop 0
	global_load_dwordx4 v[56:59], v[56:57], off offset:16
	v_add_f32_e32 v100, v100, v101
	v_mul_f32_e32 v101, v77, v77
	v_mul_f32_e32 v102, v79, v79
	v_fmac_f32_e32 v101, v76, v76
	v_fmac_f32_e32 v102, v78, v78
	v_add_f32_e32 v101, v101, v102
	v_add_f32_e32 v100, v100, v101
	s_waitcnt vmcnt(11)
	v_mul_f32_e32 v101, v81, v81
	v_mul_f32_e32 v102, v83, v83
	v_fmac_f32_e32 v101, v80, v80
	v_fmac_f32_e32 v102, v82, v82
	v_add_f32_e32 v101, v101, v102
	v_add_f32_e32 v100, v100, v101
	s_waitcnt vmcnt(10)
	v_mul_f32_e32 v101, v73, v73
	v_mul_f32_e32 v102, v75, v75
	v_fmac_f32_e32 v101, v72, v72
	v_fmac_f32_e32 v102, v74, v74
	v_add_f32_e32 v101, v101, v102
	v_add_f32_e32 v100, v100, v101
	s_waitcnt vmcnt(9)
	v_mul_f32_e32 v101, v69, v69
	v_mul_f32_e32 v102, v71, v71
	v_fmac_f32_e32 v101, v68, v68
	v_fmac_f32_e32 v102, v70, v70
	v_add_f32_e32 v101, v101, v102
	v_add_f32_e32 v100, v100, v101
	s_waitcnt vmcnt(8)
	v_mul_f32_e32 v101, v65, v65
	v_mul_f32_e32 v102, v67, v67
	v_fmac_f32_e32 v101, v64, v64
	v_fmac_f32_e32 v102, v66, v66
	v_add_f32_e32 v101, v101, v102
	v_add_f32_e32 v100, v100, v101
	s_nop 1
	v_add_f32_dpp v100, v100, v100 quad_perm:[1,0,3,2] row_mask:0xf bank_mask:0xf
	s_nop 1
	v_add_f32_dpp v100, v100, v100 quad_perm:[2,3,0,1] row_mask:0xf bank_mask:0xf
	s_nop 1
	v_add_f32_dpp v100, v100, v100 row_half_mirror row_mask:0xf bank_mask:0xf
	s_nop 1
	v_add_f32_dpp v100, v100, v100 row_mirror row_mask:0xf bank_mask:0xf
	v_mov_b32_e32 v101, v100
	s_nop 1
	v_permlane16_swap_b32_e32 v100, v101
	v_add_f32_e32 v100, v100, v101
	v_mov_b32_e32 v101, v100
	s_nop 1
	v_permlane32_swap_b32_e32 v100, v101
	v_add_f32_e32 v100, v100, v101
	v_readlane_b32 s40, v254, 11
	v_readlane_b32 s41, v254, 12
	v_readlane_b32 s42, v254, 13
	v_readlane_b32 s43, v254, 14
	v_readlane_b32 s44, v254, 15
	v_readlane_b32 s45, v254, 16
	v_readlane_b32 s46, v254, 17
	v_readlane_b32 s47, v254, 18
	v_readlane_b32 s48, v254, 19
	v_readlane_b32 s49, v254, 20
	v_readlane_b32 s50, v254, 21
	v_readlane_b32 s51, v254, 22
	v_fmamk_f32 v100, v100, 0x3a000000, v109
	v_mul_f32_e32 v101, 0x4f800000, v100
	v_cmp_gt_f32_e32 vcc, s23, v100
	s_nop 1
	v_cndmask_b32_e32 v100, v100, v101, vcc
	v_sqrt_f32_e32 v101, v100
	s_nop 0
	v_add_u32_e32 v102, -1, v101
	v_fma_f32 v112, -v102, v101, v100
	v_cmp_ge_f32_e64 s[6:7], 0, v112
	v_add_u32_e32 v112, 1, v101
	s_nop 0
	v_cndmask_b32_e64 v102, v101, v102, s[6:7]
	v_fma_f32 v101, -v112, v101, v100
	v_cmp_lt_f32_e64 s[6:7], 0, v101
	s_nop 1
	v_cndmask_b32_e64 v101, v102, v112, s[6:7]
	v_mul_f32_e32 v102, 0x37800000, v101
	v_cndmask_b32_e32 v101, v101, v102, vcc
	v_cmp_class_f32_e32 vcc, v100, v110
	s_nop 1
	v_cndmask_b32_e32 v100, v101, v100, vcc
	v_div_scale_f32 v101, s[6:7], v100, v100, 1.0
	v_rcp_f32_e32 v102, v101
	s_nop 0
	v_fma_f32 v112, -v101, v102, 1.0
	v_fmac_f32_e32 v102, v112, v102
	v_div_scale_f32 v112, vcc, 1.0, v100, 1.0
	v_mul_f32_e32 v113, v112, v102
	v_fma_f32 v114, -v101, v113, v112
	v_fmac_f32_e32 v113, v114, v102
	v_fma_f32 v101, -v101, v113, v112
	v_div_fmas_f32 v101, v101, v102, v113
	s_and_saveexec_b64 s[6:7], s[4:5]
	s_xor_b64 s[6:7], exec, s[6:7]
	s_ashr_i32 s21, s20, 31
	s_or_saveexec_b64 s[6:7], s[6:7]
	v_div_fixup_f32 v102, v101, v100, 1.0
	v_mov_b64_e32 v[100:101], s[20:21]
	s_xor_b64 exec, exec, s[6:7]
	s_cbranch_execz .LBB0_33
	v_mul_f32_e32 v100, 0x42fe0000, v102
	v_div_scale_f32 v101, s[20:21], v100, v100, s25
	v_rcp_f32_e32 v112, v101
	v_div_scale_f32 v113, vcc, s25, v100, s25
	s_add_u32 s20, s58, s16
	v_fma_f32 v114, -v101, v112, 1.0
	v_fmac_f32_e32 v112, v114, v112
	v_mul_f32_e32 v114, v113, v112
	v_fma_f32 v115, -v101, v114, v113
	v_fmac_f32_e32 v114, v115, v112
	v_fma_f32 v101, -v101, v114, v113
	v_div_fmas_f32 v101, v101, v112, v114
	v_div_fixup_f32 v100, v101, v100, s25
	s_addc_u32 s21, s59, s17
	global_store_dword v111, v100, s[12:13]
	v_mov_b64_e32 v[100:101], s[20:21]
; __device__ __forceinline__ void p0_prep(Frame& F) {
;     ...
;           f32x4 xa[4], xb4[4]; float am = 0.f;
; #pragma unroll
;           for (int j = 0; j < 4; ++j) { const f32x4 ga = g1a[j], gb = g1b[j];
;               xa[j] = cur[j][0] * rstd * ga; xb4[j] = cur[j][1] * rstd * gb;
; #pragma unroll
;               for (int c = 0; c < 4; ++c) am = fmaxf(am, fmaxf(fabsf(xa[j][c]), fabsf(xb4[j][c]))); }
.LBB0_33:
	s_or_b64 exec, exec, s[6:7]
	v_pk_mul_f32 v[92:93], v[92:93], v[102:103] op_sel_hi:[1,0]
	v_pk_mul_f32 v[84:85], v[84:85], v[102:103] op_sel_hi:[1,0]
	v_pk_mul_f32 v[94:95], v[94:95], v[102:103] op_sel_hi:[1,0]
	v_pk_mul_f32 v[92:93], v[4:5], v[92:93]
	v_pk_mul_f32 v[86:87], v[86:87], v[102:103] op_sel_hi:[1,0]
	v_pk_mul_f32 v[84:85], v[0:1], v[84:85]
	v_pk_mul_f32 v[94:95], v[6:7], v[94:95]
	v_pk_mul_f32 v[86:87], v[2:3], v[86:87]
	v_max_f32_e64 v112, |v92|, |v84|
	v_max_f32_e64 v113, |v93|, |v85|
	v_pk_mul_f32 v[88:89], v[88:89], v[102:103] op_sel_hi:[1,0]
	v_pk_mul_f32 v[76:77], v[76:77], v[102:103] op_sel_hi:[1,0]
	v_max3_f32 v112, v112, 0, v113
	v_max_f32_e64 v113, |v94|, |v86|
	v_max_f32_e64 v114, |v95|, |v87|
	v_pk_mul_f32 v[90:91], v[90:91], v[102:103] op_sel_hi:[1,0]
	v_pk_mul_f32 v[88:89], v[12:13], v[88:89]
	v_pk_mul_f32 v[78:79], v[78:79], v[102:103] op_sel_hi:[1,0]
	v_pk_mul_f32 v[76:77], v[8:9], v[76:77]
	v_max3_f32 v112, v112, v113, v114
	v_pk_mul_f32 v[90:91], v[14:15], v[90:91]
	v_pk_mul_f32 v[78:79], v[10:11], v[78:79]
	v_max_f32_e64 v113, |v88|, |v76|
	v_max_f32_e64 v114, |v89|, |v77|
	v_pk_mul_f32 v[80:81], v[80:81], v[102:103] op_sel_hi:[1,0]
	v_pk_mul_f32 v[72:73], v[72:73], v[102:103] op_sel_hi:[1,0]
	v_max3_f32 v112, v112, v113, v114
	v_max_f32_e64 v113, |v90|, |v78|
	v_max_f32_e64 v114, |v91|, |v79|
	v_pk_mul_f32 v[82:83], v[82:83], v[102:103] op_sel_hi:[1,0]
	v_pk_mul_f32 v[80:81], v[16:17], v[80:81]
	v_pk_mul_f32 v[74:75], v[74:75], v[102:103] op_sel_hi:[1,0]
	v_pk_mul_f32 v[72:73], v[20:21], v[72:73]
	v_max3_f32 v112, v112, v113, v114
	v_pk_mul_f32 v[82:83], v[18:19], v[82:83]
	v_pk_mul_f32 v[74:75], v[22:23], v[74:75]
	v_max_f32_e64 v113, |v80|, |v72|
	v_max_f32_e64 v114, |v81|, |v73|
	v_max3_f32 v112, v112, v113, v114
	v_max_f32_e64 v113, |v82|, |v74|
	v_max_f32_e64 v114, |v83|, |v75|
	v_pk_mul_f32 v[68:69], v[68:69], v[102:103] op_sel_hi:[1,0]
	v_pk_mul_f32 v[64:65], v[64:65], v[102:103] op_sel_hi:[1,0]
	v_max3_f32 v114, v112, v113, v114
	v_pk_mul_f32 v[70:71], v[70:71], v[102:103] op_sel_hi:[1,0]
	v_pk_mul_f32 v[68:69], v[24:25], v[68:69]
	v_pk_mul_f32 v[66:67], v[66:67], v[102:103] op_sel_hi:[1,0]
	v_pk_mul_f32 v[112:113], v[28:29], v[64:65]
	v_pk_mul_f32 v[70:71], v[26:27], v[70:71]
	v_pk_mul_f32 v[66:67], v[30:31], v[66:67]
	v_max_f32_e64 v64, |v68|, |v112|
	v_max_f32_e64 v65, |v69|, |v113|
	v_max3_f32 v64, v114, v64, v65
	v_max_f32_e64 v65, |v70|, |v66|
	v_max_f32_e64 v102, |v71|, |v67|
	v_max3_f32 v64, v64, v65, v102
	s_waitcnt lgkmcnt(0)
; __device__ __forceinline__ void p0_prep(Frame& F) {
;     ...
; #pragma unroll
;           for (int o = 1; o < 64; o <<= 1) am = fmaxf(am, __shfl_xor(am, o));
;           const float inv = am > 0.f ? 127.0f / am : 0.f;
; #pragma unroll
;           for (int j = 0; j < 4; ++j) { v2u o; unsigned w0 = 0, w1 = 0;
; #pragma unroll
;               for (int c = 0; c < 4; ++c) { w0 |= ((unsigned)(int)__builtin_rintf(xa[j][c] * inv) & 0xffu) << (8 * c); w1 |= ((unsigned)(int)__builtin_rintf(xb4[j][c] * inv) & 0xffu) << (8 * c); }
;               o.x = w0; o.y = w1; *(v2u*)((unsigned char*)XN + (size_t)t * DM + 512 * j + 8 * lane) = o; }
;           if (lane == 0) ((float*)(F.ws + WS_SXN))[t] = am > 0.f ? am * (1.0f / 127.0f) : 1.0f;
	s_nop 1
	v_max_f32_dpp v64, v64, v64 quad_perm:[1,0,3,2] row_mask:0xf bank_mask:0xf
	s_nop 1
	v_max_f32_dpp v64, v64, v64 quad_perm:[2,3,0,1] row_mask:0xf bank_mask:0xf
	s_nop 1
	v_max_f32_dpp v64, v64, v64 row_half_mirror row_mask:0xf bank_mask:0xf
	s_nop 1
	v_max_f32_dpp v64, v64, v64 row_mirror row_mask:0xf bank_mask:0xf
	v_mov_b32_e32 v65, v64
	s_nop 1
	v_permlane16_swap_b32_e32 v64, v65
	v_max_f32_e32 v64, v64, v65
	v_mov_b32_e32 v65, v64
	s_nop 1
	v_permlane32_swap_b32_e32 v64, v65
	v_max_f32_e32 v64, v64, v65
	v_div_scale_f32 v65, s[6:7], v64, v64, s24
	v_rcp_f32_e32 v102, v65
	s_nop 0
	v_fma_f32 v114, -v65, v102, 1.0
	v_fmac_f32_e32 v102, v114, v102
	v_div_scale_f32 v114, vcc, s24, v64, s24
	v_mul_f32_e32 v115, v114, v102
	v_fma_f32 v116, -v65, v115, v114
	v_fmac_f32_e32 v115, v116, v102
	v_fma_f32 v65, -v65, v115, v114
	v_div_fmas_f32 v65, v65, v102, v115
	v_div_fixup_f32 v65, v65, v64, s24
	v_cmp_lt_f32_e32 vcc, 0, v64
	v_lshlrev_b64 v[114:115], 11, v[100:101]
	v_lshl_add_u64 v[114:115], v[98:99], 0, v[114:115]
	v_cndmask_b32_e32 v65, 0, v65, vcc
	v_mul_f32_e32 v93, v93, v65
	v_rndne_f32_e32 v93, v93
	v_cvt_i32_f32_e32 v93, v93
	v_mul_f32_e32 v84, v84, v65
	v_rndne_f32_e32 v84, v84
	v_mul_f32_e32 v85, v85, v65
	v_mul_f32_e32 v92, v92, v65
	v_cvt_i32_f32_e32 v102, v84
	v_lshlrev_b32_e32 v84, 8, v93
	v_rndne_f32_e32 v85, v85
	v_mul_f32_e32 v93, v94, v65
	v_mul_f32_e32 v86, v86, v65
	v_mul_f32_e32 v94, v95, v65
	v_mul_f32_e32 v87, v87, v65
	v_rndne_f32_e32 v92, v92
	v_cvt_i32_f32_e32 v85, v85
	v_rndne_f32_e32 v93, v93
	v_rndne_f32_e32 v86, v86
	v_rndne_f32_e32 v94, v94
	v_rndne_f32_e32 v87, v87
	v_cvt_i32_f32_e32 v92, v92
	v_cvt_i32_f32_sdwa v93, v93 dst_sel:WORD_1 dst_unused:UNUSED_PAD src0_sel:DWORD
	v_cvt_i32_f32_sdwa v86, v86 dst_sel:WORD_1 dst_unused:UNUSED_PAD src0_sel:DWORD
	v_cvt_i32_f32_e32 v94, v94
	v_cvt_i32_f32_e32 v87, v87
	v_lshlrev_b32_e32 v85, 8, v85
	v_and_b32_e32 v84, 0xff00, v84
	v_and_b32_e32 v85, 0xff00, v85
	v_and_b32_e32 v93, 0xff0000, v93
	v_and_b32_e32 v86, 0xff0000, v86
	v_perm_b32 v92, v94, v92, s26
	v_perm_b32 v87, v87, v102, s26
	v_or3_b32 v84, v92, v84, v93
	v_or3_b32 v85, v87, v85, v86
	global_store_dwordx2 v[114:115], v[84:85], off
	v_mul_f32_e32 v85, v89, v65
	v_rndne_f32_e32 v85, v85
	v_cvt_i32_f32_e32 v85, v85
	v_mul_f32_e32 v76, v76, v65
	v_rndne_f32_e32 v76, v76
	v_mul_f32_e32 v77, v77, v65
	v_mul_f32_e32 v84, v88, v65
	v_cvt_i32_f32_e32 v86, v76
	v_lshlrev_b32_e32 v76, 8, v85
	v_rndne_f32_e32 v77, v77
	v_mul_f32_e32 v85, v90, v65
	v_mul_f32_e32 v78, v78, v65
	v_mul_f32_e32 v87, v91, v65
	v_mul_f32_e32 v79, v79, v65
	v_rndne_f32_e32 v84, v84
	v_cvt_i32_f32_e32 v77, v77
	v_rndne_f32_e32 v85, v85
	v_rndne_f32_e32 v78, v78
	v_rndne_f32_e32 v87, v87
	v_rndne_f32_e32 v79, v79
	v_cvt_i32_f32_e32 v84, v84
	v_cvt_i32_f32_sdwa v85, v85 dst_sel:WORD_1 dst_unused:UNUSED_PAD src0_sel:DWORD
	v_cvt_i32_f32_sdwa v78, v78 dst_sel:WORD_1 dst_unused:UNUSED_PAD src0_sel:DWORD
	v_cvt_i32_f32_e32 v87, v87
	v_cvt_i32_f32_e32 v79, v79
	v_lshlrev_b32_e32 v77, 8, v77
	v_and_b32_e32 v76, 0xff00, v76
	v_and_b32_e32 v77, 0xff00, v77
	v_and_b32_e32 v85, 0xff0000, v85
	v_and_b32_e32 v78, 0xff0000, v78
	v_perm_b32 v84, v87, v84, s26
	v_perm_b32 v79, v79, v86, s26
	v_or3_b32 v76, v84, v76, v85
	v_or3_b32 v77, v79, v77, v78
	global_store_dwordx2 v[114:115], v[76:77], off offset:512
	v_mul_f32_e32 v77, v81, v65
	v_rndne_f32_e32 v77, v77
	v_cvt_i32_f32_e32 v77, v77
	v_mul_f32_e32 v72, v72, v65
	v_rndne_f32_e32 v72, v72
	v_mul_f32_e32 v73, v73, v65
	v_mul_f32_e32 v76, v80, v65
	v_cvt_i32_f32_e32 v78, v72
	v_lshlrev_b32_e32 v72, 8, v77
	v_rndne_f32_e32 v73, v73
	v_mul_f32_e32 v77, v82, v65
	v_mul_f32_e32 v74, v74, v65
	v_mul_f32_e32 v79, v83, v65
	v_mul_f32_e32 v75, v75, v65
	v_rndne_f32_e32 v76, v76
	v_cvt_i32_f32_e32 v73, v73
	v_rndne_f32_e32 v77, v77
	v_rndne_f32_e32 v74, v74
	v_rndne_f32_e32 v79, v79
	v_rndne_f32_e32 v75, v75
	v_cvt_i32_f32_e32 v76, v76
	v_cvt_i32_f32_sdwa v77, v77 dst_sel:WORD_1 dst_unused:UNUSED_PAD src0_sel:DWORD
	v_cvt_i32_f32_sdwa v74, v74 dst_sel:WORD_1 dst_unused:UNUSED_PAD src0_sel:DWORD
	v_cvt_i32_f32_e32 v79, v79
	v_cvt_i32_f32_e32 v75, v75
	v_lshlrev_b32_e32 v73, 8, v73
	v_and_b32_e32 v72, 0xff00, v72
	v_and_b32_e32 v73, 0xff00, v73
	v_and_b32_e32 v77, 0xff0000, v77
	v_and_b32_e32 v74, 0xff0000, v74
	v_perm_b32 v76, v79, v76, s26
	v_perm_b32 v75, v75, v78, s26
	v_or3_b32 v72, v76, v72, v77
	v_or3_b32 v73, v75, v73, v74
	global_store_dwordx2 v[114:115], v[72:73], off offset:1024
	v_mul_f32_e32 v69, v69, v65
	v_mul_f32_e32 v73, v113, v65
	v_mul_f32_e32 v68, v68, v65
	v_rndne_f32_e32 v69, v69
	v_mul_f32_e32 v72, v112, v65
	v_rndne_f32_e32 v73, v73
	v_mul_f32_e32 v70, v70, v65
	v_mul_f32_e32 v66, v66, v65
	v_mul_f32_e32 v71, v71, v65
	v_mul_f32_e32 v65, v67, v65
	v_rndne_f32_e32 v68, v68
	v_cvt_i32_f32_e32 v69, v69
	v_rndne_f32_e32 v72, v72
	v_cvt_i32_f32_e32 v73, v73
	v_rndne_f32_e32 v70, v70
	v_rndne_f32_e32 v66, v66
	v_rndne_f32_e32 v71, v71
	v_rndne_f32_e32 v65, v65
	v_cvt_i32_f32_e32 v68, v68
	v_cvt_i32_f32_e32 v72, v72
	v_cvt_i32_f32_sdwa v70, v70 dst_sel:WORD_1 dst_unused:UNUSED_PAD src0_sel:DWORD
	v_cvt_i32_f32_sdwa v66, v66 dst_sel:WORD_1 dst_unused:UNUSED_PAD src0_sel:DWORD
	v_cvt_i32_f32_e32 v71, v71
	v_cvt_i32_f32_e32 v65, v65
	v_lshlrev_b32_e32 v69, 8, v69
	v_lshlrev_b32_e32 v73, 8, v73
	v_and_b32_e32 v69, 0xff00, v69
	v_and_b32_e32 v73, 0xff00, v73
	v_and_b32_e32 v70, 0xff0000, v70
	v_and_b32_e32 v67, 0xff0000, v66
	v_perm_b32 v66, v71, v68, s26
	v_perm_b32 v65, v65, v72, s26
	v_or3_b32 v66, v66, v69, v70
	v_or3_b32 v67, v65, v73, v67
	global_store_dwordx2 v[114:115], v[66:67], off offset:1536
	s_and_saveexec_b64 s[6:7], s[0:1]
	s_cbranch_execz .LBB0_28
	v_mul_f32_e32 v64, 0x3c010204, v64
	v_lshl_add_u64 v[66:67], v[100:101], 2, s[8:9]
	v_cndmask_b32_e32 v64, 1.0, v64, vcc
	global_store_dword v[66:67], v64, off
	s_branch .LBB0_28
